# E37: norm row loops keep w/sc/sh in registers and reload only when the row class changes, on top of E36
# speedup vs baseline: 1.0036x; 1.0020x over previous
; __device__ __forceinline__ int tid_() { int t = threadIdx.x; asm volatile("" : "+v"(t)); return t; }
; __device__ __forceinline__ void norm_phase(float* __restrict__ X, bf16_t* __restrict__ H, const float* __restrict__ nw, const float* __restrict__ modL, const float* __restrict__ modC, int sh_off, int sc_off, ...
;   const int tid = tid_(); const int wid = tid >> 6, lane = tid & 63;
;   const int stride = gridDim.x * 8;
;   int r = blockIdx.x * 8 + wid;
;   f32x4 nx[4];
;     ...
;   if (r < T_TOK) { const float* sp = NSRC(r);
; #pragma unroll
;     for (int i = 0; i < 4; ++i) nx[i] = *(const f32x4*)(sp + i * 256 + lane * 4);
;   }
;   for (; r < T_TOK; r += stride) {
;     float* xr = X + (size_t)r * DM; f32x4 v[4]; float ss = 0.f;
; #pragma unroll
;     for (int i = 0; i < 4; ++i) v[i] = nx[i];
;     const int rn = r + stride;
;     if (rn < T_TOK) { const float* sp = NSRC(rn);
; #pragma unroll
;       for (int i = 0; i < 4; ++i) nx[i] = *(const f32x4*)(sp + i * 256 + lane * 4);
;     }
.LBB0_534:
	s_or_b64 exec, exec, s[24:25]
	v_readlane_b32 s28, v255, 28
	v_readlane_b32 s29, v255, 29
	v_lshlrev_b32_e32 v2, 2, v4
	s_mov_b32 s29, s35
	v_and_b32_e32 v36, 0xfc, v2
	s_lshl_b64 s[24:25], s[28:29], 12
	v_lshlrev_b32_e32 v6, 2, v36
	v_mov_b32_e32 v7, v144
	s_waitcnt lgkmcnt(0)
	s_add_u32 s24, s22, s24
	v_lshl_add_u64 v[0:1], v[0:1], 0, v[6:7]
	s_addc_u32 s25, s23, s25
	global_load_dwordx4 v[28:31], v[0:1], off
	global_load_dwordx4 v[24:27], v[0:1], off offset:1024
	global_load_dwordx4 v[20:23], v[0:1], off offset:2048
	global_load_dwordx4 v[32:35], v[0:1], off offset:3072
	s_nop 0
	global_load_dwordx4 v[0:3], v6, s[24:25]
	s_mul_i32 s23, s28, 0x6000
	s_mul_hi_u32 s22, s28, 0x6000
	s_mov_b32 s36, s28
	s_add_u32 s20, s20, s23
	v_writelane_b32 v255, s36, 28
	s_addc_u32 s21, s21, s22
	v_lshl_add_u64 v[38:39], s[24:25], 0, v[6:7]
	v_writelane_b32 v255, s37, 29
	s_add_u32 s36, s20, 0x9b90000
	s_addc_u32 s37, s21, 0
	v_readlane_b32 s20, v255, 30
	v_readlane_b32 s21, v255, 31
	s_lshl_b64 s[20:21], s[20:21], 2
	s_add_u32 s18, s18, s20
	s_addc_u32 s19, s19, s21
	s_add_u32 s38, s18, 0x9b96000
	s_addc_u32 s39, s19, 0
	v_and_b32_e32 v7, 63, v4
	v_lshlrev_b64 v[12:13], 11, v[56:57]
	s_cmp_lg_u64 s[14:15], 0
	v_lshl_or_b32 v12, v7, 3, v12
	s_cselect_b64 s[20:21], -1, 0
	s_cmp_lg_u64 s[10:11], 0
	v_or_b32_e32 v6, 0x100, v36
	v_or_b32_e32 v8, 0x200, v36
	v_or_b32_e32 v10, 0x300, v36
	v_lshlrev_b64 v[4:5], 12, v[56:57]
	v_lshl_add_u64 v[12:13], s[6:7], 0, v[12:13]
	s_mov_b64 s[6:7], 0x4100000
	s_mov_b64 s[18:19], 0
	s_cselect_b64 s[22:23], -1, 0
	v_lshlrev_b32_e32 v40, 4, v7
	v_mov_b32_e32 v41, v144
	v_lshl_add_u64 v[42:43], s[26:27], 0, v[4:5]
	v_lshl_add_u64 v[44:45], v[12:13], 0, s[6:7]
	v_lshl_add_u64 v[46:47], s[8:9], 0, v[4:5]
	v_lshlrev_b32_e32 v48, 2, v6
	v_lshlrev_b32_e32 v50, 2, v8
	v_lshlrev_b32_e32 v52, 2, v10
	s_waitcnt vmcnt(1)
	s_mov_b32 s101, -1
	s_branch .LBB0_536

; __device__ __forceinline__ void store_bf16x4(bf16_t* p, f32x4 v) { u32x2 w; w.x = cvt_pk_bf16(v[0], v[1]); w.y = cvt_pk_bf16(v[2], v[3]); *(u32x2*)p = w; }
; __device__ __forceinline__ void norm_phase(float* __restrict__ X, bf16_t* __restrict__ H, const float* __restrict__ nw, const float* __restrict__ modL, const float* __restrict__ modC, int sh_off, int sc_off, ...
;     ...
;   for (; r < T_TOK; r += stride) {
;     float* xr = X + (size_t)r * DM; f32x4 v[4]; float ss = 0.f;
; #pragma unroll
;     for (int i = 0; i < 4; ++i) v[i] = nx[i];
;     const int rn = r + stride;
;     if (rn < T_TOK) { const float* sp = NSRC(rn);
; #pragma unroll
;       for (int i = 0; i < 4; ++i) nx[i] = *(const f32x4*)(sp + i * 256 + lane * 4);
;     }
;     if (r < NCTX && nsl > 0) {
;       for (int sl = 0; sl < nsl; ++sl) { const float* pr = part + ((size_t)sl * NCTX + r) * DM;
; #pragma unroll
;         for (int i = 0; i < 4; ++i) v[i] += *(const f32x4*)(pr + i * 256 + lane * 4); }
; #pragma unroll
;       for (int i = 0; i < 4; ++i) *(f32x4*)(xr + i * 256 + lane * 4) = v[i];
;     }
; #pragma unroll
;     for (int i = 0; i < 4; ++i) ss += v[i][0] * v[i][0] + v[i][1] * v[i][1] + v[i][2] * v[i][2] + v[i][3] * v[i][3];
;     ss = wave_sum(ss); const float rstd = rsqrtf(ss * (1.f / DM) + EPSN);
;     const float* md = r < NCTX ? modC : modL;
; #pragma unroll
;     for (int i = 0; i < 4; ++i) { const int col = i * 256 + lane * 4; const f32x4 w = *(const f32x4*)(nw + col), sc = *(const f32x4*)(md + sc_off + col), sh = *(const f32x4*)(md + sh_off + col);
;       f32x4 h; for (int j = 0; j < 4; ++j) h[j] = (v[i][j] * rstd) * w[j] * (1.f + sc[j]) + sh[j];
;       store_bf16x4(H + (size_t)r * DM + col, h); }
;   }
.Lnrm_pf_n1:
	s_waitcnt vmcnt(4)
	v_mul_f32_e32 v28, v28, v37
	v_mul_f32_e32 v29, v29, v37
	v_mul_f32_e32 v30, v30, v37
	v_mul_f32_e32 v31, v31, v37
	v_mul_f32_e32 v28, v0, v28
	v_mul_f32_e32 v29, v1, v29
	v_mul_f32_e32 v30, v2, v30
	v_mul_f32_e32 v31, v3, v31
	v_add_f32_e32 v232, 1.0, v162
	v_add_f32_e32 v233, 1.0, v163
	v_add_f32_e32 v234, 1.0, v164
	v_add_f32_e32 v235, 1.0, v165
	v_fma_f32 v28, v232, v28, v178
	v_fma_f32 v29, v233, v29, v179
	v_fma_f32 v30, v234, v30, v180
	v_fma_f32 v31, v235, v31, v181
	v_cvt_pk_bf16_f32 v60, v28, v29
	v_cvt_pk_bf16_f32 v61, v30, v31
	global_store_dwordx2 v[44:45], v[60:61], off
	v_mul_f32_e32 v24, v24, v37
	v_mul_f32_e32 v25, v25, v37
	v_mul_f32_e32 v26, v26, v37
	v_mul_f32_e32 v27, v27, v37
	v_mul_f32_e32 v24, v150, v24
	v_mul_f32_e32 v25, v151, v25
	v_mul_f32_e32 v26, v152, v26
	v_mul_f32_e32 v27, v153, v27
	v_add_f32_e32 v232, 1.0, v166
	v_add_f32_e32 v233, 1.0, v167
	v_add_f32_e32 v234, 1.0, v168
	v_add_f32_e32 v235, 1.0, v169
	v_fma_f32 v24, v232, v24, v182
	v_fma_f32 v25, v233, v25, v183
	v_fma_f32 v26, v234, v26, v184
	v_fma_f32 v27, v235, v27, v185
	v_cvt_pk_bf16_f32 v62, v24, v25
	v_cvt_pk_bf16_f32 v63, v26, v27
	global_store_dwordx2 v[44:45], v[62:63], off offset:512
	v_mul_f32_e32 v20, v20, v37
	v_mul_f32_e32 v21, v21, v37
	v_mul_f32_e32 v22, v22, v37
	v_mul_f32_e32 v23, v23, v37
	v_mul_f32_e32 v20, v154, v20
	v_mul_f32_e32 v21, v155, v21
	v_mul_f32_e32 v22, v156, v22
	v_mul_f32_e32 v23, v157, v23
	v_add_f32_e32 v232, 1.0, v170
	v_add_f32_e32 v233, 1.0, v171
	v_add_f32_e32 v234, 1.0, v172
	v_add_f32_e32 v235, 1.0, v173
	v_fma_f32 v20, v232, v20, v214
	v_fma_f32 v21, v233, v21, v215
	v_fma_f32 v22, v234, v22, v216
	v_fma_f32 v23, v235, v23, v217
	v_cvt_pk_bf16_f32 v64, v20, v21
	v_cvt_pk_bf16_f32 v65, v22, v23
	global_store_dwordx2 v[44:45], v[64:65], off offset:1024
	v_mul_f32_e32 v32, v32, v37
	v_mul_f32_e32 v33, v33, v37
	v_mul_f32_e32 v34, v34, v37
	v_mul_f32_e32 v35, v35, v37
	v_mul_f32_e32 v32, v158, v32
	v_mul_f32_e32 v33, v159, v33
	v_mul_f32_e32 v34, v160, v34
	v_mul_f32_e32 v35, v161, v35
	v_add_f32_e32 v232, 1.0, v174
	v_add_f32_e32 v233, 1.0, v175
	v_add_f32_e32 v234, 1.0, v176
	v_add_f32_e32 v235, 1.0, v177
	v_fma_f32 v32, v232, v32, v218
	v_fma_f32 v33, v233, v33, v219
	v_fma_f32 v34, v234, v34, v220
	v_fma_f32 v35, v235, v35, v221
	v_cvt_pk_bf16_f32 v66, v32, v33
	v_cvt_pk_bf16_f32 v67, v34, v35
	global_store_dwordx2 v[44:45], v[66:67], off offset:1536
	s_waitcnt vmcnt(4)
	v_mov_b32_e32 v28, v16
	v_mov_b32_e32 v29, v17
	v_mov_b32_e32 v30, v18
	v_mov_b32_e32 v31, v19
	v_mov_b32_e32 v24, v12
	v_mov_b32_e32 v25, v13
	v_mov_b32_e32 v26, v14
	v_mov_b32_e32 v27, v15
	v_mov_b32_e32 v20, v8
	v_mov_b32_e32 v21, v9
	v_mov_b32_e32 v22, v10
	v_mov_b32_e32 v23, v11
	v_mov_b32_e32 v32, v4
	v_mov_b32_e32 v33, v5
	v_mov_b32_e32 v34, v6
	v_mov_b32_e32 v35, v7
	v_mov_b32_e32 v56, v54
	v_lshl_add_u64 v[44:45], v[44:45], 0, s[6:7]
	s_andn2_b64 exec, exec, s[18:19]
	s_cbranch_execz .LBB0_550
.LBB0_536:
	v_add_u32_e32 v54, s50, v56
	v_cmp_gt_i32_e32 vcc, s86, v54
	v_cmp_lt_i32_e64 s[6:7], s79, v54
	v_readfirstlane_b32 s100, v56
	s_nop 0
	s_cmp_gt_i32 s100, 0xff
	s_cselect_b32 s100, 1, 0
	s_cmp_eq_u32 s100, s101
	s_cbranch_scc1 .Lgam_skip_n1
	s_mov_b32 s101, s100
	v_cmp_gt_i32_e64 s[24:25], s73, v56
	v_mov_b32_e32 v222, s37
	v_mov_b32_e32 v223, s39
	v_cndmask_b32_e64 v225, v222, v223, s[24:25]
	v_mov_b32_e32 v222, s36
	v_mov_b32_e32 v223, s38
	v_cndmask_b32_e64 v224, v222, v223, s[24:25]
	v_lshlrev_b32_e32 v226, 2, v36
	v_mov_b32_e32 v227, v144
	v_lshl_add_u64 v[224:225], v[224:225], 0, v[226:227]
	s_mov_b64 s[24:25], 0x1000
	v_lshl_add_u64 v[228:229], v[224:225], 0, s[24:25]
	v_lshl_add_u64 v[230:231], v[224:225], 0, 0
	global_load_dwordx4 v[162:165], v[228:229], off
	global_load_dwordx4 v[178:181], v[230:231], off
	global_load_dwordx4 v[150:153], v[38:39], off offset:1024
	global_load_dwordx4 v[166:169], v[228:229], off offset:1024
	global_load_dwordx4 v[182:185], v[230:231], off offset:1024
	global_load_dwordx4 v[154:157], v[38:39], off offset:2048
	global_load_dwordx4 v[170:173], v[228:229], off offset:2048
	global_load_dwordx4 v[214:217], v[230:231], off offset:2048
	global_load_dwordx4 v[158:161], v[38:39], off offset:3072
	global_load_dwordx4 v[174:177], v[228:229], off offset:3072
	global_load_dwordx4 v[218:221], v[230:231], off offset:3072
.Lgam_skip_n1:
	s_or_b32 s32, vcc_lo, vcc_hi
	s_and_saveexec_b64 s[26:27], vcc
	s_cbranch_execz .LBB0_546
	v_cmp_lt_i32_e32 vcc, s81, v54
	s_and_saveexec_b64 s[24:25], vcc
	s_xor_b64 s[24:25], exec, s[24:25]
	s_cbranch_execz .LBB0_541
	s_andn2_b64 vcc, exec, s[20:21]
	s_cbranch_vccnz .LBB0_548
	v_add_u32_e32 v4, 0xffffff00, v54
	v_mov_b32_e32 v5, v144
	v_lshlrev_b64 v[4:5], 12, v[4:5]
	v_lshl_add_u64 v[4:5], s[14:15], 0, v[4:5]
	s_cbranch_execnz .LBB0_541

; __device__ __forceinline__ int tid_() { int t = threadIdx.x; asm volatile("" : "+v"(t)); return t; }
; __device__ __forceinline__ void norm_phase(float* __restrict__ X, bf16_t* __restrict__ H, const float* __restrict__ nw, const float* __restrict__ modL, const float* __restrict__ modC, int sh_off, int sc_off, ...
;   const int tid = tid_(); const int wid = tid >> 6, lane = tid & 63;
;   const int stride = gridDim.x * 8;
;   int r = blockIdx.x * 8 + wid;
;   f32x4 nx[4];
;     ...
;   if (r < T_TOK) { const float* sp = NSRC(r);
; #pragma unroll
;     for (int i = 0; i < 4; ++i) nx[i] = *(const f32x4*)(sp + i * 256 + lane * 4);
;   }
;   for (; r < T_TOK; r += stride) {
;     float* xr = X + (size_t)r * DM; f32x4 v[4]; float ss = 0.f;
; #pragma unroll
;     for (int i = 0; i < 4; ++i) v[i] = nx[i];
;     const int rn = r + stride;
;     if (rn < T_TOK) { const float* sp = NSRC(rn);
; #pragma unroll
;       for (int i = 0; i < 4; ++i) nx[i] = *(const f32x4*)(sp + i * 256 + lane * 4);
;     }
.LBB0_2699:
	s_or_b64 exec, exec, s[24:25]
	v_lshlrev_b32_e32 v2, 2, v6
	v_and_b32_e32 v36, 0xfc, v2
	s_lshl_b64 s[24:25], s[34:35], 12
	v_lshlrev_b32_e32 v12, 2, v36
	v_mov_b32_e32 v13, v144
	s_waitcnt lgkmcnt(0)
	s_add_u32 s22, s22, s24
	v_lshl_add_u64 v[0:1], v[0:1], 0, v[12:13]
	s_addc_u32 s23, s23, s25
	global_load_dwordx4 v[32:35], v[0:1], off
	global_load_dwordx4 v[28:31], v[0:1], off offset:1024
	global_load_dwordx4 v[24:27], v[0:1], off offset:2048
	global_load_dwordx4 v[8:11], v[0:1], off offset:3072
	s_nop 0
	global_load_dwordx4 v[0:3], v12, s[22:23]
	v_readlane_b32 s24, v255, 30
	v_readlane_b32 s25, v255, 31
	s_lshl_b64 s[24:25], s[24:25], 2
	s_add_u32 s18, s18, s24
	s_addc_u32 s19, s19, s25
	s_add_u32 s26, s18, 0x9b90000
	s_addc_u32 s27, s19, 0
	s_lshl_b64 s[18:19], s[4:5], 2
	s_add_u32 s16, s16, s18
	s_addc_u32 s17, s17, s19
	s_add_u32 s28, s16, 0x9b90000
	v_lshl_add_u64 v[38:39], s[22:23], 0, v[12:13]
	v_and_b32_e32 v13, 63, v6
	v_lshlrev_b64 v[6:7], 11, v[56:57]
	s_addc_u32 s29, s17, 0
	v_lshl_or_b32 v6, v13, 3, v6
	s_cmp_lg_u64 s[14:15], 0
	v_or_b32_e32 v12, 0x100, v36
	v_or_b32_e32 v14, 0x200, v36
	v_or_b32_e32 v16, 0x300, v36
	v_lshl_add_u64 v[6:7], s[8:9], 0, v[6:7]
	s_mov_b64 s[8:9], 0x4100000
	s_mov_b64 s[16:17], 0
	s_cselect_b64 s[18:19], -1, 0
	v_lshlrev_b32_e32 v40, 4, v13
	v_mov_b32_e32 v41, v144
	v_lshl_add_u64 v[42:43], s[20:21], 0, v[4:5]
	v_lshl_add_u64 v[44:45], v[6:7], 0, s[8:9]
	v_lshl_add_u64 v[46:47], s[10:11], 0, v[4:5]
	v_lshlrev_b32_e32 v48, 2, v12
	v_lshlrev_b32_e32 v50, 2, v14
	v_lshlrev_b32_e32 v52, 2, v16
	s_waitcnt vmcnt(1)
	s_mov_b32 s101, -1
	s_branch .LBB0_2701

; __device__ __forceinline__ void store_bf16x4(bf16_t* p, f32x4 v) { u32x2 w; w.x = cvt_pk_bf16(v[0], v[1]); w.y = cvt_pk_bf16(v[2], v[3]); *(u32x2*)p = w; }
; __device__ __forceinline__ void norm_phase(float* __restrict__ X, bf16_t* __restrict__ H, const float* __restrict__ nw, const float* __restrict__ modL, const float* __restrict__ modC, int sh_off, int sc_off, ...
;     ...
;   for (; r < T_TOK; r += stride) {
;     float* xr = X + (size_t)r * DM; f32x4 v[4]; float ss = 0.f;
; #pragma unroll
;     for (int i = 0; i < 4; ++i) v[i] = nx[i];
;     const int rn = r + stride;
;     if (rn < T_TOK) { const float* sp = NSRC(rn);
; #pragma unroll
;       for (int i = 0; i < 4; ++i) nx[i] = *(const f32x4*)(sp + i * 256 + lane * 4);
;     }
;     if (r < NCTX && nsl > 0) {
;       for (int sl = 0; sl < nsl; ++sl) { const float* pr = part + ((size_t)sl * NCTX + r) * DM;
; #pragma unroll
;         for (int i = 0; i < 4; ++i) v[i] += *(const f32x4*)(pr + i * 256 + lane * 4); }
; #pragma unroll
;       for (int i = 0; i < 4; ++i) *(f32x4*)(xr + i * 256 + lane * 4) = v[i];
;     }
; #pragma unroll
;     for (int i = 0; i < 4; ++i) ss += v[i][0] * v[i][0] + v[i][1] * v[i][1] + v[i][2] * v[i][2] + v[i][3] * v[i][3];
;     ss = wave_sum(ss); const float rstd = rsqrtf(ss * (1.f / DM) + EPSN);
;     const float* md = r < NCTX ? modC : modL;
; #pragma unroll
;     for (int i = 0; i < 4; ++i) { const int col = i * 256 + lane * 4; const f32x4 w = *(const f32x4*)(nw + col), sc = *(const f32x4*)(md + sc_off + col), sh = *(const f32x4*)(md + sh_off + col);
;       f32x4 h; for (int j = 0; j < 4; ++j) h[j] = (v[i][j] * rstd) * w[j] * (1.f + sc[j]) + sh[j];
;       store_bf16x4(H + (size_t)r * DM + col, h); }
;   }
.Lnrm_pf_n2:
	s_waitcnt vmcnt(4)
	v_mul_f32_e32 v32, v32, v37
	v_mul_f32_e32 v33, v33, v37
	v_mul_f32_e32 v34, v34, v37
	v_mul_f32_e32 v35, v35, v37
	v_mul_f32_e32 v32, v0, v32
	v_mul_f32_e32 v33, v1, v33
	v_mul_f32_e32 v34, v2, v34
	v_mul_f32_e32 v35, v3, v35
	v_add_f32_e32 v232, 1.0, v162
	v_add_f32_e32 v233, 1.0, v163
	v_add_f32_e32 v234, 1.0, v164
	v_add_f32_e32 v235, 1.0, v165
	v_fma_f32 v32, v232, v32, v178
	v_fma_f32 v33, v233, v33, v179
	v_fma_f32 v34, v234, v34, v180
	v_fma_f32 v35, v235, v35, v181
	v_cvt_pk_bf16_f32 v60, v32, v33
	v_cvt_pk_bf16_f32 v61, v34, v35
	global_store_dwordx2 v[44:45], v[60:61], off
	v_mul_f32_e32 v28, v28, v37
	v_mul_f32_e32 v29, v29, v37
	v_mul_f32_e32 v30, v30, v37
	v_mul_f32_e32 v31, v31, v37
	v_mul_f32_e32 v28, v150, v28
	v_mul_f32_e32 v29, v151, v29
	v_mul_f32_e32 v30, v152, v30
	v_mul_f32_e32 v31, v153, v31
	v_add_f32_e32 v232, 1.0, v166
	v_add_f32_e32 v233, 1.0, v167
	v_add_f32_e32 v234, 1.0, v168
	v_add_f32_e32 v235, 1.0, v169
	v_fma_f32 v28, v232, v28, v182
	v_fma_f32 v29, v233, v29, v183
	v_fma_f32 v30, v234, v30, v184
	v_fma_f32 v31, v235, v31, v185
	v_cvt_pk_bf16_f32 v62, v28, v29
	v_cvt_pk_bf16_f32 v63, v30, v31
	global_store_dwordx2 v[44:45], v[62:63], off offset:512
	v_mul_f32_e32 v24, v24, v37
	v_mul_f32_e32 v25, v25, v37
	v_mul_f32_e32 v26, v26, v37
	v_mul_f32_e32 v27, v27, v37
	v_mul_f32_e32 v24, v154, v24
	v_mul_f32_e32 v25, v155, v25
	v_mul_f32_e32 v26, v156, v26
	v_mul_f32_e32 v27, v157, v27
	v_add_f32_e32 v232, 1.0, v170
	v_add_f32_e32 v233, 1.0, v171
	v_add_f32_e32 v234, 1.0, v172
	v_add_f32_e32 v235, 1.0, v173
	v_fma_f32 v24, v232, v24, v214
	v_fma_f32 v25, v233, v25, v215
	v_fma_f32 v26, v234, v26, v216
	v_fma_f32 v27, v235, v27, v217
	v_cvt_pk_bf16_f32 v64, v24, v25
	v_cvt_pk_bf16_f32 v65, v26, v27
	global_store_dwordx2 v[44:45], v[64:65], off offset:1024
	v_mul_f32_e32 v8, v8, v37
	v_mul_f32_e32 v9, v9, v37
	v_mul_f32_e32 v10, v10, v37
	v_mul_f32_e32 v11, v11, v37
	v_mul_f32_e32 v8, v158, v8
	v_mul_f32_e32 v9, v159, v9
	v_mul_f32_e32 v10, v160, v10
	v_mul_f32_e32 v11, v161, v11
	v_add_f32_e32 v232, 1.0, v174
	v_add_f32_e32 v233, 1.0, v175
	v_add_f32_e32 v234, 1.0, v176
	v_add_f32_e32 v235, 1.0, v177
	v_fma_f32 v8, v232, v8, v218
	v_fma_f32 v9, v233, v9, v219
	v_fma_f32 v10, v234, v10, v220
	v_fma_f32 v11, v235, v11, v221
	v_cvt_pk_bf16_f32 v66, v8, v9
	v_cvt_pk_bf16_f32 v67, v10, v11
	global_store_dwordx2 v[44:45], v[66:67], off offset:1536
	s_waitcnt vmcnt(4)
	v_mov_b32_e32 v32, v20
	v_mov_b32_e32 v33, v21
	v_mov_b32_e32 v34, v22
	v_mov_b32_e32 v35, v23
	v_mov_b32_e32 v28, v16
	v_mov_b32_e32 v29, v17
	v_mov_b32_e32 v30, v18
	v_mov_b32_e32 v31, v19
	v_mov_b32_e32 v24, v12
	v_mov_b32_e32 v25, v13
	v_mov_b32_e32 v26, v14
	v_mov_b32_e32 v27, v15
	v_mov_b32_e32 v8, v4
	v_mov_b32_e32 v9, v5
	v_mov_b32_e32 v10, v6
	v_mov_b32_e32 v11, v7
	v_mov_b32_e32 v56, v54
	v_lshl_add_u64 v[44:45], v[44:45], 0, s[8:9]
	s_andn2_b64 exec, exec, s[16:17]
	s_cbranch_execz .LBB0_2712
.LBB0_2701:
	v_add_u32_e32 v54, s50, v56
	v_cmp_gt_i32_e32 vcc, s86, v54
	v_cmp_lt_i32_e64 s[8:9], s79, v54
	v_readfirstlane_b32 s100, v56
	s_nop 0
	s_cmp_gt_i32 s100, 0xff
	s_cselect_b32 s100, 1, 0
	s_cmp_eq_u32 s100, s101
	s_cbranch_scc1 .Lgam_skip_n2
	s_mov_b32 s101, s100
	v_cmp_lt_i32_e64 s[22:23], s81, v56
	v_mov_b32_e32 v222, s29
	v_mov_b32_e32 v223, s27
	v_cndmask_b32_e64 v225, v222, v223, s[22:23]
	v_mov_b32_e32 v222, s28
	v_mov_b32_e32 v223, s26
	v_cndmask_b32_e64 v224, v222, v223, s[22:23]
	v_lshlrev_b32_e32 v226, 2, v36
	v_mov_b32_e32 v227, v144
	v_lshl_add_u64 v[224:225], v[224:225], 0, v[226:227]
	s_mov_b64 s[22:23], 0x4000
	v_lshl_add_u64 v[228:229], v[224:225], 0, s[22:23]
	s_mov_b64 s[22:23], 0x3000
	v_lshl_add_u64 v[230:231], v[224:225], 0, s[22:23]
	global_load_dwordx4 v[162:165], v[228:229], off
	global_load_dwordx4 v[178:181], v[230:231], off
	global_load_dwordx4 v[150:153], v[38:39], off offset:1024
	global_load_dwordx4 v[166:169], v[228:229], off offset:1024
	global_load_dwordx4 v[182:185], v[230:231], off offset:1024
	global_load_dwordx4 v[154:157], v[38:39], off offset:2048
	global_load_dwordx4 v[170:173], v[228:229], off offset:2048
	global_load_dwordx4 v[214:217], v[230:231], off offset:2048
	global_load_dwordx4 v[158:161], v[38:39], off offset:3072
	global_load_dwordx4 v[174:177], v[228:229], off offset:3072
	global_load_dwordx4 v[218:221], v[230:231], off offset:3072
.Lgam_skip_n2:
	s_or_b32 s32, vcc_lo, vcc_hi
	s_and_saveexec_b64 s[20:21], vcc
	s_cbranch_execz .LBB0_2709
	v_cmp_lt_i32_e32 vcc, s81, v54
	s_and_saveexec_b64 s[22:23], vcc
	s_xor_b64 s[22:23], exec, s[22:23]
	v_mov_b32_e32 v55, v144
	v_lshlrev_b64 v[4:5], 12, v[54:55]
	v_lshl_add_u64 v[4:5], s[10:11], 0, v[4:5]
	s_andn2_saveexec_b64 s[22:23], s[22:23]
	s_cbranch_execz .LBB0_2708
	v_ashrrev_i32_e32 v55, 31, v54
	s_andn2_b64 vcc, exec, s[18:19]
	v_lshlrev_b64 v[6:7], 12, v[54:55]
	s_cbranch_vccnz .LBB0_2711
	v_lshl_add_u64 v[4:5], s[14:15], 0, v[6:7]
	s_cbranch_execnz .LBB0_2708

; __global__ void __launch_bounds__(512) fwd_megakernel(Params Parg) {
	.amdhsa_kernel _Z14fwd_megakernel6Params
		.amdhsa_group_segment_fixed_size 16
		.amdhsa_private_segment_fixed_size 0
		.amdhsa_kernarg_size 480
		.amdhsa_user_sgpr_count 2
		.amdhsa_user_sgpr_dispatch_ptr 0
		.amdhsa_user_sgpr_queue_ptr 0
		.amdhsa_user_sgpr_kernarg_segment_ptr 1
		.amdhsa_user_sgpr_dispatch_id 0
		.amdhsa_user_sgpr_kernarg_preload_length 0
		.amdhsa_user_sgpr_kernarg_preload_offset 0
		.amdhsa_user_sgpr_private_segment_size 0
		.amdhsa_uses_dynamic_stack 0
		.amdhsa_enable_private_segment 0
		.amdhsa_system_sgpr_workgroup_id_x 1
		.amdhsa_system_sgpr_workgroup_id_y 0
		.amdhsa_system_sgpr_workgroup_id_z 0
		.amdhsa_system_sgpr_workgroup_info 0
		.amdhsa_system_vgpr_workitem_id 2
		.amdhsa_next_free_vgpr 256
		.amdhsa_next_free_sgpr 102
		.amdhsa_accum_offset 256
		.amdhsa_reserve_vcc 1
		.amdhsa_float_round_mode_32 0
		.amdhsa_float_round_mode_16_64 0
		.amdhsa_float_denorm_mode_32 3
		.amdhsa_float_denorm_mode_16_64 3
		.amdhsa_dx10_clamp 1
		.amdhsa_ieee_mode 1
		.amdhsa_fp16_overflow 0
		.amdhsa_tg_split 0
		.amdhsa_exception_fp_ieee_invalid_op 0
		.amdhsa_exception_fp_denorm_src 0
		.amdhsa_exception_fp_ieee_div_zero 0
		.amdhsa_exception_fp_ieee_overflow 0
		.amdhsa_exception_fp_ieee_underflow 0
		.amdhsa_exception_fp_ieee_inexact 0
		.amdhsa_exception_int_div_zero 0
	.end_amdhsa_kernel

; __global__ void __launch_bounds__(512) fwd_megakernel(Params Parg) {
amdhsa.kernels:
  - .agpr_count:     0
    .args:
      - .offset:         0
        .size:           224
        .value_kind:     by_value
      - .offset:         224
        .size:           4
        .value_kind:     hidden_block_count_x
      - .offset:         228
        .size:           4
        .value_kind:     hidden_block_count_y
      - .offset:         232
        .size:           4
        .value_kind:     hidden_block_count_z
      - .offset:         236
        .size:           2
        .value_kind:     hidden_group_size_x
      - .offset:         238
        .size:           2
        .value_kind:     hidden_group_size_y
      - .offset:         240
        .size:           2
        .value_kind:     hidden_group_size_z
      - .offset:         242
        .size:           2
        .value_kind:     hidden_remainder_x
      - .offset:         244
        .size:           2
        .value_kind:     hidden_remainder_y
      - .offset:         246
        .size:           2
        .value_kind:     hidden_remainder_z
      - .offset:         264
        .size:           8
        .value_kind:     hidden_global_offset_x
      - .offset:         272
        .size:           8
        .value_kind:     hidden_global_offset_y
      - .offset:         280
        .size:           8
        .value_kind:     hidden_global_offset_z
      - .offset:         288
        .size:           2
        .value_kind:     hidden_grid_dims
      - .offset:         312
        .size:           8
        .value_kind:     hidden_multigrid_sync_arg
      - .offset:         344
        .size:           4
        .value_kind:     hidden_dynamic_lds_size
    .group_segment_fixed_size: 16
    .kernarg_segment_align: 8
    .kernarg_segment_size: 480
    .language:       OpenCL C
    .language_version:
      - 2
      - 0
    .max_flat_workgroup_size: 512
    .name:           _Z14fwd_megakernel6Params
    .private_segment_fixed_size: 0
    .sgpr_count:     108
    .sgpr_spill_count: 118
    .symbol:         _Z14fwd_megakernel6Params.kd
    .uniform_work_group_size: 1
    .uses_dynamic_stack: false
    .vgpr_count:     256
    .vgpr_spill_count: 0
    .wavefront_size: 64
